# norm loops (f32 and bf16 input): early vmcnt(0) after the first row's loads dropped so all row loads of an iteration are in flight together; on v91
# speedup vs baseline: 1.0037x; 1.0037x over previous
; #define GAS __attribute__((address_space(1)))
; __device__ __forceinline__ float sumsq8(const u32x4 w) { const f32x4 a = unpack_lo4(w), b = unpack_hi4(w); return ((a.x * a.x + a.y * a.y) + (a.z * a.z + a.w * a.w)) + ((b.x * b.x + b.y * b.y) + (b.z * b.z + b.w * b.w)); }
; template <int R> __device__ __forceinline__ void norm_rows_bf16in(const bf16* x, bf16* o, int m0, int rstride, const float* g, const float* shift, const float* scale, int lane) {
;     u32x4 v[R][2]; float s[R];
; #pragma unroll
;     for (int r = 0; r < R; ++r) { const GAS u32x4* xr = (const GAS u32x4*)(x + (size_t)(m0 + r * rstride) * D) + lane; v[r][0] = __builtin_nontemporal_load(xr); v[r][1] = __builtin_nontemporal_load(xr + 64); }
; #pragma unroll
;     for (int r = 0; r < R; ++r) { s[r] = 0.f;
; #pragma unroll
;         for (int j = 0; j < 2; ++j) s[r] += sumsq8(v[r][j]); }
; #pragma unroll
;     for (int of = 1; of < 64; of <<= 1) {
; #pragma unroll
;         for (int r = 0; r < R; ++r) s[r] += __shfl_xor(s[r], of); }
; #pragma unroll
;     for (int j = 0; j < 2; ++j) {
;         const int i4 = 2 * (lane + 64 * j);
;         const f32x4 g0 = ((const GAS f32x4*)g)[i4], g1 = ((const GAS f32x4*)g)[i4 + 1], h0 = ((const GAS f32x4*)shift)[i4], h1 = ((const GAS f32x4*)shift)[i4 + 1], c0 = ((const GAS f32x4*)scale)[i4], c1 = ((const GAS f32x4*)scale)[i4 + 1];
;         const f32x4 gs0 = g0 * (c0 + 1.0f), gs1 = g1 * (c1 + 1.0f);
.LBB0_124:
	v_cmp_lt_i32_e32 vcc, v214, v213
	s_add_i32 s8, s16, s14
	s_mov_b32 s4, 0
	v_cndmask_b32_e32 v0, v212, v214, vcc
	v_cmp_lt_i32_e32 vcc, v215, v213
	v_lshl_add_u64 v[22:23], s[72:73], 0, v[74:75]
	global_load_dwordx4 v[18:21], v[22:23], off offset:1024 nt
	global_load_dwordx4 v[14:17], v[22:23], off nt
	v_cndmask_b32_e32 v5, v212, v215, vcc
	v_cmp_lt_i32_e32 vcc, v216, v213
	s_ashr_i32 s5, s8, 13
	s_brev_b32 s6, 7
	v_cndmask_b32_e32 v6, v212, v216, vcc
	v_cmp_lt_i32_e32 vcc, v217, v213
	s_mul_hi_i32 s9, s4, 0xc8
	s_mul_i32 s10, s4, 0xc8
	v_cndmask_b32_e32 v7, v212, v217, vcc
	v_cmp_lt_i32_e32 vcc, v218, v213
	v_lshlrev_b32_e32 v145, 2, v0
	v_lshlrev_b32_e32 v144, 2, v5
	v_cndmask_b32_e32 v8, v212, v218, vcc
	v_cmp_lt_i32_e32 vcc, v219, v213
	v_lshlrev_b32_e32 v143, 2, v6
	v_lshlrev_b32_e32 v142, 2, v7
	v_cndmask_b32_e32 v9, v212, v219, vcc
	v_add_co_u32_e32 v26, vcc, s6, v22
	s_mul_i32 s6, s5, 0x2400
	s_ashr_i32 s7, s6, 31
	s_lshl_b64 s[4:5], s[6:7], 2
	s_add_u32 s4, s13, s4
	s_addc_u32 s5, s18, s5
	s_add_u32 s6, s0, s10
	v_lshl_add_u64 v[24:25], s[4:5], 0, v[76:77]
	s_addc_u32 s7, s1, s9
	v_lshlrev_b32_e32 v5, 2, v8
	v_lshlrev_b32_e32 v0, 2, v9
	global_load_dwordx4 v[6:9], v[24:25], off offset:16
	global_load_dwordx4 v[10:13], v[24:25], off
	s_load_dwordx2 s[6:7], s[6:7], 0x20
	v_lshl_add_u64 v[28:29], s[4:5], 0, v[78:79]
	v_addc_co_u32_e32 v27, vcc, -1, v23, vcc
	s_waitcnt lgkmcnt(0)
	s_add_u32 s6, s6, s70
	s_addc_u32 s7, s7, s71
	s_add_u32 s4, s4, 0x1000
	v_lshl_add_u64 v[30:31], s[6:7], 0, v[76:77]
	v_lshl_add_u64 v[62:63], s[6:7], 0, v[78:79]
	s_addc_u32 s5, s5, 0
	s_add_i32 s6, s8, 0x800
	s_ashr_i32 s7, s6, 31
	v_lshl_add_u64 v[72:73], s[4:5], 0, v[76:77]
	s_nop 0
	v_lshl_add_u64 v[80:81], s[4:5], 0, v[78:79]
	s_lshl_b64 s[4:5], s[6:7], 11
	s_add_u32 s6, s56, s4
	s_addc_u32 s7, s57, s5
	s_add_i32 s10, s8, 0x1000
	global_load_dwordx4 v[48:51], v[30:31], off offset:16
	global_load_dwordx4 v[52:55], v[30:31], off
	global_load_dwordx4 v[56:59], v[72:73], off
	global_load_dwordx4 v[64:67], v[72:73], off offset:16
	v_lshl_add_u64 v[32:33], s[6:7], 0, v[74:75]
	s_ashr_i32 s11, s10, 31
	global_load_dwordx4 v[68:71], v[32:33], off offset:1024 nt
	global_load_dwordx4 v[82:85], v[32:33], off nt
	s_lshl_b64 s[6:7], s[10:11], 11
	s_add_u32 s10, s56, s6
	s_addc_u32 s11, s57, s7
	s_addk_i32 s8, 0x1800
	v_lshl_add_u64 v[32:33], s[10:11], 0, v[74:75]
	s_ashr_i32 s9, s8, 31
	global_load_dwordx4 v[88:91], v[32:33], off nt
	global_load_dwordx4 v[92:95], v[32:33], off offset:1024 nt
	s_lshl_b64 s[8:9], s[8:9], 11
	s_add_u32 s10, s56, s8
	s_addc_u32 s11, s57, s9
	v_lshl_add_u64 v[32:33], s[10:11], 0, v[74:75]
	global_load_dwordx4 v[138:141], v[32:33], off nt
	global_load_dwordx4 v[146:149], v[32:33], off offset:1024 nt
	s_add_u32 s4, s62, s4
	s_addc_u32 s5, s63, s5
	v_lshl_add_u64 v[32:33], s[4:5], 0, v[74:75]
	s_add_u32 s4, s62, s6
	s_addc_u32 s5, s63, s7
	v_lshl_add_u64 v[34:35], s[4:5], 0, v[74:75]
	s_add_u32 s4, s62, s8
	s_addc_u32 s5, s63, s9
	v_lshl_add_u64 v[36:37], s[4:5], 0, v[74:75]
	s_addk_i32 s14, 0x2000
	s_add_u32 s72, s72, 0x1000000
	s_addc_u32 s73, s73, 0
	s_waitcnt vmcnt(0)
	v_lshlrev_b32_e32 v41, 16, v18
	v_lshlrev_b32_e32 v40, 16, v14
	v_and_b32_e32 v39, 0xffff0000, v18
	v_and_b32_e32 v38, 0xffff0000, v14
	v_lshlrev_b32_e32 v43, 16, v19
	v_lshlrev_b32_e32 v42, 16, v15
	v_and_b32_e32 v19, 0xffff0000, v19
	v_and_b32_e32 v18, 0xffff0000, v15
	v_lshlrev_b32_e32 v45, 16, v20
	v_and_b32_e32 v15, 0xffff0000, v20
	v_and_b32_e32 v14, 0xffff0000, v16
	v_lshlrev_b32_e32 v47, 16, v21
	v_and_b32_e32 v21, 0xffff0000, v21
	v_and_b32_e32 v20, 0xffff0000, v17
	v_lshlrev_b32_e32 v44, 16, v16
	v_lshlrev_b32_e32 v46, 16, v17
	v_pk_mul_f32 v[16:17], v[38:39], v[38:39]
	v_pk_mul_f32 v[60:61], v[18:19], v[18:19]
	v_pk_mul_f32 v[86:87], v[14:15], v[14:15]
	v_pk_mul_f32 v[96:97], v[20:21], v[20:21]
	v_pk_fma_f32 v[16:17], v[40:41], v[40:41], v[16:17]
	v_pk_fma_f32 v[60:61], v[42:43], v[42:43], v[60:61]
	v_pk_fma_f32 v[86:87], v[44:45], v[44:45], v[86:87]
	v_pk_fma_f32 v[96:97], v[46:47], v[46:47], v[96:97]
	v_pk_add_f32 v[16:17], v[16:17], v[60:61]
	v_pk_add_f32 v[60:61], v[86:87], v[96:97]
	v_mov_b32_e32 v129, v14
	v_pk_add_f32 v[16:17], v[16:17], v[60:61]
	v_mov_b32_e32 v135, v18
	v_add_f32_e32 v14, v16, v17
	ds_bpermute_b32 v16, v145, v14
	v_mov_b32_e32 v131, v20
	v_mov_b32_e32 v133, v38
	v_mov_b32_e32 v132, v40
	v_mov_b32_e32 v134, v42
	s_waitcnt lgkmcnt(0)
	v_add_f32_e32 v14, v14, v16
	ds_bpermute_b32 v16, v144, v14
	v_mov_b32_e32 v128, v44
	v_mov_b32_e32 v130, v46
	s_cmp_lg_u32 s14, 0x10000
	s_waitcnt lgkmcnt(0)
	v_add_f32_e32 v14, v14, v16
	ds_bpermute_b32 v18, v143, v14
	s_waitcnt lgkmcnt(0)
; #define GAS __attribute__((address_space(1)))
; __device__ __forceinline__ float sumsq8(const u32x4 w) { const f32x4 a = unpack_lo4(w), b = unpack_hi4(w); return ((a.x * a.x + a.y * a.y) + (a.z * a.z + a.w * a.w)) + ((b.x * b.x + b.y * b.y) + (b.z * b.z + b.w * b.w)); }
; template <int R> __device__ __forceinline__ void norm_rows_bf16in(const bf16* x, bf16* o, int m0, int rstride, const float* g, const float* shift, const float* scale, int lane) {
;     ...
;     for (int r = 0; r < R; ++r) { const GAS u32x4* xr = (const GAS u32x4*)(x + (size_t)(m0 + r * rstride) * D) + lane; v[r][0] = __builtin_nontemporal_load(xr); v[r][1] = __builtin_nontemporal_load(xr + 64); }
; #pragma unroll
;     for (int r = 0; r < R; ++r) { s[r] = 0.f;
; #pragma unroll
;         for (int j = 0; j < 2; ++j) s[r] += sumsq8(v[r][j]); }
; #pragma unroll
;     for (int of = 1; of < 64; of <<= 1) {
; #pragma unroll
;         for (int r = 0; r < R; ++r) s[r] += __shfl_xor(s[r], of); }
; #pragma unroll
;     for (int j = 0; j < 2; ++j) {
;         const int i4 = 2 * (lane + 64 * j);
;         const f32x4 g0 = ((const GAS f32x4*)g)[i4], g1 = ((const GAS f32x4*)g)[i4 + 1], h0 = ((const GAS f32x4*)shift)[i4], h1 = ((const GAS f32x4*)shift)[i4 + 1], c0 = ((const GAS f32x4*)scale)[i4], c1 = ((const GAS f32x4*)scale)[i4 + 1];
;         const f32x4 gs0 = g0 * (c0 + 1.0f), gs1 = g1 * (c1 + 1.0f);
; #pragma unroll
;         for (int r = 0; r < R; ++r) {
;             const float rstd = 1.0f / sqrtf(s[r] * (1.0f / D) + EPS);
	v_add_f32_e32 v14, v14, v18
	v_pk_add_f32 v[16:17], v[58:59], 1.0 op_sel_hi:[1,0]
	v_pk_add_f32 v[56:57], v[56:57], 1.0 op_sel_hi:[1,0]
	v_pk_add_f32 v[58:59], v[66:67], 1.0 op_sel_hi:[1,0]
	v_pk_add_f32 v[60:61], v[64:65], 1.0 op_sel_hi:[1,0]
	v_pk_mul_f32 v[106:107], v[54:55], v[16:17]
	v_pk_mul_f32 v[108:109], v[52:53], v[56:57]
	v_pk_mul_f32 v[110:111], v[50:51], v[58:59]
	v_pk_mul_f32 v[112:113], v[48:49], v[60:61]
	v_and_b32_e32 v17, 0xffff0000, v68
	v_and_b32_e32 v16, 0xffff0000, v82
	v_and_b32_e32 v49, 0xffff0000, v69
	v_and_b32_e32 v48, 0xffff0000, v83
	v_and_b32_e32 v51, 0xffff0000, v70
	v_and_b32_e32 v50, 0xffff0000, v84
	v_and_b32_e32 v53, 0xffff0000, v71
	v_and_b32_e32 v52, 0xffff0000, v85
	v_lshlrev_b32_e32 v55, 16, v68
	v_lshlrev_b32_e32 v54, 16, v82
	v_lshlrev_b32_e32 v57, 16, v69
	v_lshlrev_b32_e32 v56, 16, v83
	v_lshlrev_b32_e32 v59, 16, v70
	v_lshlrev_b32_e32 v58, 16, v84
	v_lshlrev_b32_e32 v61, 16, v71
	v_lshlrev_b32_e32 v60, 16, v85
	v_pk_mul_f32 v[64:65], v[16:17], v[16:17]
	v_pk_mul_f32 v[66:67], v[48:49], v[48:49]
	v_pk_mul_f32 v[68:69], v[50:51], v[50:51]
	v_pk_mul_f32 v[70:71], v[52:53], v[52:53]
	v_mov_b32_e32 v115, v16
	v_pk_fma_f32 v[64:65], v[54:55], v[54:55], v[64:65]
	v_pk_fma_f32 v[66:67], v[56:57], v[56:57], v[66:67]
	v_pk_fma_f32 v[68:69], v[58:59], v[58:59], v[68:69]
	v_pk_fma_f32 v[70:71], v[60:61], v[60:61], v[70:71]
	ds_bpermute_b32 v16, v142, v14
	v_pk_add_f32 v[64:65], v[64:65], v[66:67]
	v_pk_add_f32 v[66:67], v[68:69], v[70:71]
	v_and_b32_e32 v69, 0xffff0000, v94
	v_pk_add_f32 v[96:97], v[64:65], v[66:67]
	v_and_b32_e32 v65, 0xffff0000, v92
	v_and_b32_e32 v64, 0xffff0000, v88
	v_and_b32_e32 v67, 0xffff0000, v93
	v_and_b32_e32 v66, 0xffff0000, v89
	v_and_b32_e32 v68, 0xffff0000, v90
	v_and_b32_e32 v71, 0xffff0000, v95
	v_and_b32_e32 v70, 0xffff0000, v91
	v_lshlrev_b32_e32 v83, 16, v92
	v_lshlrev_b32_e32 v82, 16, v88
	v_lshlrev_b32_e32 v85, 16, v93
	v_lshlrev_b32_e32 v84, 16, v89
	v_lshlrev_b32_e32 v87, 16, v94
	v_lshlrev_b32_e32 v86, 16, v90
	v_lshlrev_b32_e32 v89, 16, v95
	v_lshlrev_b32_e32 v88, 16, v91
	v_add_f32_e32 v18, v96, v97
	v_pk_mul_f32 v[90:91], v[64:65], v[64:65]
	v_pk_mul_f32 v[92:93], v[66:67], v[66:67]
	v_pk_mul_f32 v[94:95], v[68:69], v[68:69]
	v_pk_mul_f32 v[96:97], v[70:71], v[70:71]
	v_pk_fma_f32 v[90:91], v[82:83], v[82:83], v[90:91]
	v_pk_fma_f32 v[92:93], v[84:85], v[84:85], v[92:93]
	v_pk_fma_f32 v[94:95], v[86:87], v[86:87], v[94:95]
	v_pk_fma_f32 v[96:97], v[88:89], v[88:89], v[96:97]
	ds_bpermute_b32 v20, v145, v18
	v_pk_add_f32 v[90:91], v[90:91], v[92:93]
	v_pk_add_f32 v[92:93], v[94:95], v[96:97]
	s_waitcnt lgkmcnt(1)
	v_add_f32_e32 v14, v14, v16
	v_pk_add_f32 v[150:151], v[90:91], v[92:93]
	ds_bpermute_b32 v16, v5, v14
	v_and_b32_e32 v91, 0xffff0000, v146
	v_and_b32_e32 v90, 0xffff0000, v138
	v_and_b32_e32 v93, 0xffff0000, v147
	v_and_b32_e32 v92, 0xffff0000, v139
	v_and_b32_e32 v95, 0xffff0000, v148
	v_and_b32_e32 v94, 0xffff0000, v140
	v_and_b32_e32 v97, 0xffff0000, v149
	v_and_b32_e32 v96, 0xffff0000, v141
	v_add_f32_e32 v38, v150, v151
	v_lshlrev_b32_e32 v99, 16, v146
	v_lshlrev_b32_e32 v98, 16, v138
	v_lshlrev_b32_e32 v101, 16, v147
	v_lshlrev_b32_e32 v100, 16, v139
	v_lshlrev_b32_e32 v103, 16, v148
	v_lshlrev_b32_e32 v102, 16, v140
	v_lshlrev_b32_e32 v105, 16, v149
	v_lshlrev_b32_e32 v104, 16, v141
	v_pk_mul_f32 v[146:147], v[90:91], v[90:91]
	v_pk_mul_f32 v[148:149], v[92:93], v[92:93]
	v_pk_mul_f32 v[152:153], v[94:95], v[94:95]
	v_pk_mul_f32 v[154:155], v[96:97], v[96:97]
	ds_bpermute_b32 v40, v145, v38
	v_pk_fma_f32 v[146:147], v[98:99], v[98:99], v[146:147]
	v_pk_fma_f32 v[148:149], v[100:101], v[100:101], v[148:149]
	v_pk_fma_f32 v[152:153], v[102:103], v[102:103], v[152:153]
	v_pk_fma_f32 v[154:155], v[104:105], v[104:105], v[154:155]
	s_waitcnt lgkmcnt(2)
	v_add_f32_e32 v18, v18, v20
	v_pk_add_f32 v[146:147], v[146:147], v[148:149]
	v_pk_add_f32 v[148:149], v[152:153], v[154:155]
	ds_bpermute_b32 v20, v144, v18
	v_pk_add_f32 v[146:147], v[146:147], v[148:149]
	s_waitcnt lgkmcnt(2)
	v_add_f32_e32 v14, v14, v16
	v_add_f32_e32 v42, v146, v147
	ds_bpermute_b32 v44, v0, v14
	ds_bpermute_b32 v16, v145, v42
	s_waitcnt lgkmcnt(3)
	v_add_f32_e32 v38, v38, v40
	ds_bpermute_b32 v40, v144, v38
	s_waitcnt lgkmcnt(3)
	v_add_f32_e32 v18, v18, v20
	ds_bpermute_b32 v20, v143, v18
	s_waitcnt lgkmcnt(3)
	v_add_f32_e32 v14, v14, v44
	s_waitcnt lgkmcnt(2)
	v_add_f32_e32 v16, v42, v16
	v_fmamk_f32 v14, v14, 0x3a800000, v220
	ds_bpermute_b32 v42, v144, v16
	s_waitcnt lgkmcnt(2)
	v_add_f32_e32 v38, v38, v40
	v_mul_f32_e32 v40, 0x4f800000, v14
	v_cmp_gt_f32_e32 vcc, s45, v14
	ds_bpermute_b32 v44, v143, v38
	s_waitcnt lgkmcnt(2)
	v_add_f32_e32 v18, v18, v20
	v_cndmask_b32_e32 v14, v14, v40, vcc
	v_sqrt_f32_e32 v20, v14
	ds_bpermute_b32 v40, v142, v18
	s_waitcnt lgkmcnt(2)
	v_add_f32_e32 v16, v16, v42
	ds_bpermute_b32 v42, v143, v16
	s_waitcnt lgkmcnt(2)
	v_add_f32_e32 v38, v38, v44
	v_add_u32_e32 v44, -1, v20
	v_mov_b32_e32 v119, v48
	v_add_u32_e32 v46, 1, v20
	v_fma_f32 v48, -v44, v20, v14
	v_mov_b32_e32 v117, v50
	v_mov_b32_e32 v121, v52
	v_fma_f32 v50, -v46, v20, v14
	ds_bpermute_b32 v52, v142, v38
	v_cmp_ge_f32_e64 s[4:5], 0, v48
	s_waitcnt lgkmcnt(2)
	v_add_f32_e32 v18, v18, v40
	ds_bpermute_b32 v40, v5, v18
	v_cndmask_b32_e64 v20, v20, v44, s[4:5]
	v_cmp_lt_f32_e64 s[4:5], 0, v50
	s_waitcnt lgkmcnt(2)
	v_add_f32_e32 v16, v16, v42
	s_waitcnt lgkmcnt(1)
	v_add_f32_e32 v38, v38, v52
	v_cndmask_b32_e64 v20, v20, v46, s[4:5]
	v_mul_f32_e32 v42, 0x37800000, v20
	v_cndmask_b32_e32 v20, v20, v42, vcc
	v_cmp_class_f32_e32 vcc, v14, v221
	ds_bpermute_b32 v42, v142, v16
	s_waitcnt lgkmcnt(1)
; __device__ __forceinline__ unsigned cvtpk(float lo, float hi) { f32x2 v = {lo, hi}; bf16x2_t b = __builtin_convertvector(v, bf16x2_t); return __builtin_bit_cast(unsigned, b); }
; #define GAS __attribute__((address_space(1)))
; __device__ __forceinline__ f32x4 unpack_lo4(const u32x4 w) { return (f32x4){bf_lo(w.x), bf_hi(w.x), bf_lo(w.y), bf_hi(w.y)}; }
; __device__ __forceinline__ f32x4 unpack_hi4(const u32x4 w) { return (f32x4){bf_lo(w.z), bf_hi(w.z), bf_lo(w.w), bf_hi(w.w)}; }
; template <int R> __device__ __forceinline__ void norm_rows_bf16in(const bf16* x, bf16* o, int m0, int rstride, const float* g, const float* shift, const float* scale, int lane) {
;     ...
;     for (int j = 0; j < 2; ++j) {
;         const int i4 = 2 * (lane + 64 * j);
;         const f32x4 g0 = ((const GAS f32x4*)g)[i4], g1 = ((const GAS f32x4*)g)[i4 + 1], h0 = ((const GAS f32x4*)shift)[i4], h1 = ((const GAS f32x4*)shift)[i4 + 1], c0 = ((const GAS f32x4*)scale)[i4], c1 = ((const GAS f32x4*)scale)[i4 + 1];
;         const f32x4 gs0 = g0 * (c0 + 1.0f), gs1 = g1 * (c1 + 1.0f);
; #pragma unroll
;         for (int r = 0; r < R; ++r) {
;             const float rstd = 1.0f / sqrtf(s[r] * (1.0f / D) + EPS);
;             const f32x4 y0 = unpack_lo4(v[r][j]) * rstd * gs0 + h0, y1 = unpack_hi4(v[r][j]) * rstd * gs1 + h1;
;             u32x4 w; w.x = cvtpk(y0.x, y0.y); w.y = cvtpk(y0.z, y0.w); w.z = cvtpk(y1.x, y1.y); w.w = cvtpk(y1.z, y1.w);
;             ((GAS u32x4*)(o + (size_t)(m0 + r * rstride) * D) + lane)[64 * j] = w;
;         }
	v_add_f32_e32 v18, v18, v40
	v_cndmask_b32_e32 v14, v20, v14, vcc
	ds_bpermute_b32 v20, v5, v38
	v_div_scale_f32 v44, s[4:5], v14, v14, 1.0
	v_rcp_f32_e32 v40, v44
	ds_bpermute_b32 v48, v0, v18
	s_waitcnt lgkmcnt(2)
	v_add_f32_e32 v16, v16, v42
	ds_bpermute_b32 v5, v5, v16
	s_waitcnt lgkmcnt(2)
	v_add_f32_e32 v20, v38, v20
	v_fma_f32 v38, -v44, v40, 1.0
	v_fmac_f32_e32 v40, v38, v40
	ds_bpermute_b32 v38, v0, v20
	v_div_scale_f32 v46, vcc, 1.0, v14, 1.0
	s_waitcnt lgkmcnt(2)
	v_add_f32_e32 v18, v18, v48
	v_mul_f32_e32 v42, v46, v40
	v_fmamk_f32 v18, v18, 0x3a800000, v220
	v_fma_f32 v48, -v44, v42, v46
	s_waitcnt lgkmcnt(1)
	v_add_f32_e32 v5, v16, v5
	v_mul_f32_e32 v16, 0x4f800000, v18
	v_cmp_gt_f32_e64 s[4:5], s45, v18
	v_fmac_f32_e32 v42, v48, v40
	v_fma_f32 v44, -v44, v42, v46
	v_cndmask_b32_e64 v16, v18, v16, s[4:5]
	ds_bpermute_b32 v18, v0, v5
	s_waitcnt lgkmcnt(1)
	v_add_f32_e32 v20, v20, v38
	v_sqrt_f32_e32 v38, v16
	v_div_fmas_f32 v0, v44, v40, v42
	v_div_fixup_f32 v0, v0, v14, 1.0
	v_fmamk_f32 v14, v20, 0x3a800000, v220
	v_mul_f32_e32 v20, 0x4f800000, v14
	v_cmp_gt_f32_e32 vcc, s45, v14
	s_waitcnt lgkmcnt(0)
	v_add_f32_e32 v5, v5, v18
	v_add_u32_e32 v18, -1, v38
	v_cndmask_b32_e32 v14, v14, v20, vcc
	v_pk_mul_f32 v[132:133], v[0:1], v[132:133] op_sel_hi:[0,1]
	v_pk_mul_f32 v[134:135], v[0:1], v[134:135] op_sel_hi:[0,1]
	v_pk_mul_f32 v[128:129], v[0:1], v[128:129] op_sel_hi:[0,1]
	v_pk_mul_f32 v[130:131], v[0:1], v[130:131] op_sel_hi:[0,1]
	v_add_u32_e32 v20, 1, v38
	v_sqrt_f32_e32 v40, v14
	v_fma_f32 v42, -v18, v38, v16
	v_pk_fma_f32 v[134:135], v[134:135], v[106:107], v[12:13]
	v_pk_fma_f32 v[132:133], v[132:133], v[108:109], v[10:11]
	v_pk_fma_f32 v[142:143], v[128:129], v[112:113], v[6:7]
	v_pk_fma_f32 v[144:145], v[130:131], v[110:111], v[8:9]
	v_fma_f32 v44, -v20, v38, v16
	v_cmp_ge_f32_e64 s[6:7], 0, v42
	v_cvt_pk_bf16_f32 v128, v132, v133
	v_cvt_pk_bf16_f32 v129, v134, v135
	v_cvt_pk_bf16_f32 v130, v142, v143
	v_cvt_pk_bf16_f32 v131, v144, v145
	v_fmamk_f32 v5, v5, 0x3a800000, v220
	v_cndmask_b32_e64 v18, v38, v18, s[6:7]
	v_cmp_lt_f32_e64 s[6:7], 0, v44
	global_store_dwordx4 v[26:27], v[128:131], off
	v_mul_f32_e32 v26, 0x4f800000, v5
	v_cmp_gt_f32_e64 s[8:9], s45, v5
	v_cndmask_b32_e64 v18, v18, v20, s[6:7]
	v_add_u32_e32 v20, -1, v40
	v_cndmask_b32_e64 v5, v5, v26, s[8:9]
	v_mul_f32_e32 v38, 0x37800000, v18
	v_add_u32_e32 v26, 1, v40
	v_sqrt_f32_e32 v27, v5
	v_cndmask_b32_e64 v18, v18, v38, s[4:5]
	v_fma_f32 v38, -v20, v40, v14
	v_fma_f32 v42, -v26, v40, v14
	v_cmp_ge_f32_e64 s[6:7], 0, v38
	v_cmp_class_f32_e64 s[4:5], v16, v221
	v_mov_b32_e32 v114, v54
	v_cndmask_b32_e64 v20, v40, v20, s[6:7]
	v_cmp_lt_f32_e64 s[6:7], 0, v42
	v_cndmask_b32_e64 v16, v18, v16, s[4:5]
	v_div_scale_f32 v18, s[4:5], v16, v16, 1.0
	v_cndmask_b32_e64 v20, v20, v26, s[6:7]
	v_add_u32_e32 v26, -1, v27
	v_mul_f32_e32 v44, 0x37800000, v20
	v_add_u32_e32 v40, 1, v27
	v_rcp_f32_e32 v42, v18
	v_cndmask_b32_e32 v20, v20, v44, vcc
	v_fma_f32 v44, -v26, v27, v5
	v_cmp_class_f32_e32 vcc, v14, v221
	v_fma_f32 v46, -v40, v27, v5
	v_cmp_ge_f32_e64 s[6:7], 0, v44
	v_cndmask_b32_e32 v14, v20, v14, vcc
	v_div_scale_f32 v20, s[10:11], v14, v14, 1.0
	v_cndmask_b32_e64 v26, v27, v26, s[6:7]
	v_cmp_lt_f32_e64 s[6:7], 0, v46
	v_fma_f32 v27, -v18, v42, 1.0
	v_rcp_f32_e32 v46, v20
	v_cndmask_b32_e64 v26, v26, v40, s[6:7]
	v_mul_f32_e32 v40, 0x37800000, v26
	v_div_scale_f32 v38, s[4:5], 1.0, v16, 1.0
	v_cndmask_b32_e64 v26, v26, v40, s[8:9]
	v_cmp_class_f32_e32 vcc, v5, v221
	v_fmac_f32_e32 v42, v27, v42
	v_mul_f32_e32 v27, v38, v42
	v_cndmask_b32_e32 v5, v26, v5, vcc
	v_fma_f32 v26, -v18, v27, v38
	v_div_scale_f32 v48, s[6:7], v5, v5, 1.0
	v_fmac_f32_e32 v27, v26, v42
	v_fma_f32 v26, -v20, v46, 1.0
	v_rcp_f32_e32 v52, v48
	v_div_scale_f32 v44, s[10:11], 1.0, v14, 1.0
	v_fmac_f32_e32 v46, v26, v46
	v_fma_f32 v18, -v18, v27, v38
	s_mov_b64 vcc, s[4:5]
	v_mul_f32_e32 v38, v44, v46
	v_div_fmas_f32 v18, v18, v42, v27
	v_fma_f32 v26, -v20, v38, v44
	v_div_fixup_f32 v40, v18, v16, 1.0
	v_fmac_f32_e32 v38, v26, v46
	v_fma_f32 v16, -v48, v52, 1.0
	v_mov_b32_e32 v118, v56
	v_mov_b32_e32 v116, v58
	v_mov_b32_e32 v120, v60
	v_div_scale_f32 v50, s[6:7], 1.0, v5, 1.0
	v_fma_f32 v18, -v20, v38, v44
	v_fmac_f32_e32 v52, v16, v52
	s_mov_b64 vcc, s[10:11]
	v_pk_mul_f32 v[26:27], v[40:41], v[118:119] op_sel_hi:[0,1]
	v_pk_mul_f32 v[114:115], v[40:41], v[114:115] op_sel_hi:[0,1]
	v_pk_mul_f32 v[116:117], v[40:41], v[116:117] op_sel_hi:[0,1]
	v_pk_mul_f32 v[118:119], v[40:41], v[120:121] op_sel_hi:[0,1]
	v_div_fmas_f32 v16, v18, v46, v38
	v_mul_f32_e32 v18, v50, v52
	v_pk_fma_f32 v[26:27], v[106:107], v[26:27], v[12:13]
	v_pk_fma_f32 v[114:115], v[108:109], v[114:115], v[10:11]
	v_pk_fma_f32 v[116:117], v[116:117], v[112:113], v[6:7]
	v_pk_fma_f32 v[118:119], v[118:119], v[110:111], v[8:9]
	v_fma_f32 v20, -v48, v18, v50
	v_mov_b32_e32 v122, v82
	v_mov_b32_e32 v123, v64
	v_mov_b32_e32 v126, v84
	v_mov_b32_e32 v127, v66
	v_mov_b32_e32 v124, v86
	v_mov_b32_e32 v125, v68
	v_mov_b32_e32 v136, v88
	v_mov_b32_e32 v137, v70
	v_cvt_pk_bf16_f32 v114, v114, v115
	v_cvt_pk_bf16_f32 v115, v26, v27
	v_cvt_pk_bf16_f32 v116, v116, v117
	v_cvt_pk_bf16_f32 v117, v118, v119
	v_div_fixup_f32 v42, v16, v14, 1.0
	v_fmac_f32_e32 v18, v20, v52
	global_store_dwordx4 v[32:33], v[114:117], off
	v_pk_mul_f32 v[26:27], v[42:43], v[126:127] op_sel_hi:[0,1]
	v_pk_mul_f32 v[118:119], v[42:43], v[136:137] op_sel_hi:[0,1]
; __device__ __forceinline__ unsigned cvtpk(float lo, float hi) { f32x2 v = {lo, hi}; bf16x2_t b = __builtin_convertvector(v, bf16x2_t); return __builtin_bit_cast(unsigned, b); }
; #define GAS __attribute__((address_space(1)))
; __device__ __forceinline__ f32x4 unpack_lo4(const u32x4 w) { return (f32x4){bf_lo(w.x), bf_hi(w.x), bf_lo(w.y), bf_hi(w.y)}; }
; __device__ __forceinline__ f32x4 unpack_hi4(const u32x4 w) { return (f32x4){bf_lo(w.z), bf_hi(w.z), bf_lo(w.w), bf_hi(w.w)}; }
; template <int R> __device__ __forceinline__ void norm_rows_bf16in(const bf16* x, bf16* o, int m0, int rstride, const float* g, const float* shift, const float* scale, int lane) {
;     ...
; #pragma unroll
;     for (int j = 0; j < 2; ++j) {
;         const int i4 = 2 * (lane + 64 * j);
;         const f32x4 g0 = ((const GAS f32x4*)g)[i4], g1 = ((const GAS f32x4*)g)[i4 + 1], h0 = ((const GAS f32x4*)shift)[i4], h1 = ((const GAS f32x4*)shift)[i4 + 1], c0 = ((const GAS f32x4*)scale)[i4], c1 = ((const GAS f32x4*)scale)[i4 + 1];
;         const f32x4 gs0 = g0 * (c0 + 1.0f), gs1 = g1 * (c1 + 1.0f);
; #pragma unroll
;         for (int r = 0; r < R; ++r) {
;             const float rstd = 1.0f / sqrtf(s[r] * (1.0f / D) + EPS);
;             const f32x4 y0 = unpack_lo4(v[r][j]) * rstd * gs0 + h0, y1 = unpack_hi4(v[r][j]) * rstd * gs1 + h1;
;             u32x4 w; w.x = cvtpk(y0.x, y0.y); w.y = cvtpk(y0.z, y0.w); w.z = cvtpk(y1.x, y1.y); w.w = cvtpk(y1.z, y1.w);
;             ((GAS u32x4*)(o + (size_t)(m0 + r * rstride) * D) + lane)[64 * j] = w;
;         }
	v_pk_mul_f32 v[114:115], v[42:43], v[122:123] op_sel_hi:[0,1]
	v_pk_mul_f32 v[116:117], v[42:43], v[124:125] op_sel_hi:[0,1]
	v_fma_f32 v14, -v48, v18, v50
	s_mov_b64 vcc, s[6:7]
	v_pk_fma_f32 v[26:27], v[106:107], v[26:27], v[12:13]
	v_pk_fma_f32 v[114:115], v[108:109], v[114:115], v[10:11]
	v_pk_fma_f32 v[116:117], v[112:113], v[116:117], v[6:7]
	v_pk_fma_f32 v[118:119], v[110:111], v[118:119], v[8:9]
	v_div_fmas_f32 v14, v14, v52, v18
	v_mov_b32_e32 v138, v100
	v_mov_b32_e32 v139, v92
	v_mov_b32_e32 v140, v98
	v_mov_b32_e32 v141, v90
	v_mov_b32_e32 v150, v102
	v_mov_b32_e32 v151, v94
	v_mov_b32_e32 v156, v104
	v_mov_b32_e32 v157, v96
	v_cvt_pk_bf16_f32 v114, v114, v115
	v_cvt_pk_bf16_f32 v115, v26, v27
	v_cvt_pk_bf16_f32 v116, v116, v117
	v_cvt_pk_bf16_f32 v117, v118, v119
	v_div_fixup_f32 v44, v14, v5, 1.0
	global_store_dwordx4 v[34:35], v[114:117], off
	v_pk_mul_f32 v[26:27], v[44:45], v[138:139] op_sel_hi:[0,1]
	v_pk_mul_f32 v[118:119], v[44:45], v[156:157] op_sel_hi:[0,1]
	v_pk_mul_f32 v[114:115], v[44:45], v[140:141] op_sel_hi:[0,1]
	v_pk_mul_f32 v[116:117], v[44:45], v[150:151] op_sel_hi:[0,1]
	v_pk_fma_f32 v[12:13], v[106:107], v[26:27], v[12:13]
	v_pk_fma_f32 v[10:11], v[108:109], v[114:115], v[10:11]
	v_pk_fma_f32 v[26:27], v[110:111], v[118:119], v[8:9]
	v_pk_fma_f32 v[8:9], v[112:113], v[116:117], v[6:7]
	v_cvt_pk_bf16_f32 v6, v10, v11
	v_cvt_pk_bf16_f32 v7, v12, v13
	v_cvt_pk_bf16_f32 v8, v8, v9
	v_cvt_pk_bf16_f32 v9, v26, v27
	global_store_dwordx4 v[36:37], v[6:9], off
	global_load_dwordx4 v[6:9], v[72:73], off offset:2048
	s_nop 0
	global_load_dwordx4 v[10:13], v[80:81], off offset:16
	global_load_dwordx4 v[106:109], v[30:31], off offset:2048
	global_load_dwordx4 v[110:113], v[62:63], off offset:16
	s_nop 0
	global_load_dwordx4 v[24:27], v[24:25], off offset:2048
	s_nop 0
	global_load_dwordx4 v[28:31], v[28:29], off offset:16
	v_mov_b32_e32 v38, v41
	v_mov_b32_e32 v18, v43
	v_mov_b32_e32 v14, v45
	v_mov_b32_e32 v20, v47
	s_brev_b32 s4, 7
	v_mov_b32_e32 v16, v55
	v_mov_b32_e32 v48, v57
	v_mov_b32_e32 v50, v59
	v_mov_b32_e32 v52, v61
	v_mov_b32_e32 v64, v83
	v_mov_b32_e32 v66, v85
	v_mov_b32_e32 v68, v87
	v_mov_b32_e32 v70, v89
	v_mov_b32_e32 v90, v99
	v_mov_b32_e32 v92, v101
	v_mov_b32_e32 v94, v103
	v_mov_b32_e32 v96, v105
	v_pk_mul_f32 v[38:39], v[0:1], v[38:39] op_sel_hi:[0,1]
	v_pk_mul_f32 v[18:19], v[0:1], v[18:19] op_sel_hi:[0,1]
	v_pk_mul_f32 v[14:15], v[0:1], v[14:15] op_sel_hi:[0,1]
	v_pk_mul_f32 v[20:21], v[0:1], v[20:21] op_sel_hi:[0,1]
	s_mov_b32 s5, -1
	v_pk_mul_f32 v[16:17], v[40:41], v[16:17] op_sel_hi:[0,1]
	v_pk_mul_f32 v[46:47], v[40:41], v[48:49] op_sel_hi:[0,1]
	v_pk_mul_f32 v[48:49], v[40:41], v[50:51] op_sel_hi:[0,1]
	v_pk_mul_f32 v[40:41], v[40:41], v[52:53] op_sel_hi:[0,1]
	v_pk_mul_f32 v[50:51], v[42:43], v[64:65] op_sel_hi:[0,1]
	v_pk_mul_f32 v[52:53], v[42:43], v[66:67] op_sel_hi:[0,1]
	v_pk_mul_f32 v[54:55], v[42:43], v[68:69] op_sel_hi:[0,1]
	v_pk_mul_f32 v[42:43], v[42:43], v[70:71] op_sel_hi:[0,1]
	v_pk_mul_f32 v[56:57], v[44:45], v[90:91] op_sel_hi:[0,1]
	v_pk_mul_f32 v[58:59], v[44:45], v[92:93] op_sel_hi:[0,1]
	v_pk_mul_f32 v[60:61], v[44:45], v[94:95] op_sel_hi:[0,1]
	v_pk_mul_f32 v[44:45], v[44:45], v[96:97] op_sel_hi:[0,1]
	v_lshl_add_u64 v[22:23], v[22:23], 0, s[4:5]
	s_waitcnt vmcnt(5)
	v_pk_add_f32 v[8:9], v[8:9], 1.0 op_sel_hi:[1,0]
	v_pk_add_f32 v[6:7], v[6:7], 1.0 op_sel_hi:[1,0]
	s_waitcnt vmcnt(4)
	v_pk_add_f32 v[12:13], v[12:13], 1.0 op_sel_hi:[1,0]
	v_pk_add_f32 v[10:11], v[10:11], 1.0 op_sel_hi:[1,0]
	s_waitcnt vmcnt(3)
	v_pk_mul_f32 v[8:9], v[108:109], v[8:9]
	v_pk_mul_f32 v[6:7], v[106:107], v[6:7]
	s_waitcnt vmcnt(2)
	v_pk_mul_f32 v[12:13], v[112:113], v[12:13]
	v_pk_mul_f32 v[10:11], v[110:111], v[10:11]
	s_waitcnt vmcnt(1)
	v_pk_fma_f32 v[18:19], v[18:19], v[8:9], v[26:27]
	v_pk_fma_f32 v[38:39], v[38:39], v[6:7], v[24:25]
	s_waitcnt vmcnt(0)
	v_pk_fma_f32 v[20:21], v[20:21], v[12:13], v[30:31]
	v_pk_fma_f32 v[14:15], v[14:15], v[10:11], v[28:29]
	v_pk_fma_f32 v[46:47], v[46:47], v[8:9], v[26:27]
	v_pk_fma_f32 v[16:17], v[16:17], v[6:7], v[24:25]
	v_pk_fma_f32 v[40:41], v[40:41], v[12:13], v[30:31]
	v_pk_fma_f32 v[48:49], v[48:49], v[10:11], v[28:29]
	v_pk_fma_f32 v[52:53], v[52:53], v[8:9], v[26:27]
	v_pk_fma_f32 v[50:51], v[50:51], v[6:7], v[24:25]
	v_pk_fma_f32 v[42:43], v[42:43], v[12:13], v[30:31]
	v_pk_fma_f32 v[54:55], v[54:55], v[10:11], v[28:29]
	v_pk_fma_f32 v[26:27], v[58:59], v[8:9], v[26:27]
	v_pk_fma_f32 v[24:25], v[56:57], v[6:7], v[24:25]
	v_pk_fma_f32 v[30:31], v[44:45], v[12:13], v[30:31]
	v_pk_fma_f32 v[28:29], v[60:61], v[10:11], v[28:29]
	v_cvt_pk_bf16_f32 v6, v38, v39
	v_cvt_pk_bf16_f32 v7, v18, v19
	v_cvt_pk_bf16_f32 v8, v14, v15
	v_cvt_pk_bf16_f32 v9, v20, v21
	v_cvt_pk_bf16_f32 v10, v16, v17
	v_cvt_pk_bf16_f32 v11, v46, v47
	v_cvt_pk_bf16_f32 v12, v48, v49
	v_cvt_pk_bf16_f32 v13, v40, v41
	v_cvt_pk_bf16_f32 v14, v50, v51
	v_cvt_pk_bf16_f32 v15, v52, v53
	v_cvt_pk_bf16_f32 v16, v54, v55
	v_cvt_pk_bf16_f32 v17, v42, v43
	v_cvt_pk_bf16_f32 v18, v24, v25
	v_cvt_pk_bf16_f32 v19, v26, v27
	v_cvt_pk_bf16_f32 v20, v28, v29
	v_cvt_pk_bf16_f32 v21, v30, v31
	global_store_dwordx4 v[22:23], v[6:9], off offset:1024
	global_store_dwordx4 v[32:33], v[10:13], off offset:1024
	global_store_dwordx4 v[34:35], v[14:17], off offset:1024
	global_store_dwordx4 v[36:37], v[18:21], off offset:1024
	s_cbranch_scc1 .LBB0_124
	s_mov_b64 s[4:5], 0

; #define GAS __attribute__((address_space(1)))
; template <int R> __device__ __forceinline__ void norm_rows_bf16(const float* x, bf16* o, int m0, int rstride, const float* g, const float* shift, const float* scale, int lane) {
;     f32x4 v[R][4]; float s[R];
; #pragma unroll
;     for (int r = 0; r < R; ++r) { const GAS f32x4* xr = (const GAS f32x4*)(x + (size_t)(m0 + r * rstride) * D) + lane;
; #pragma unroll
;         for (int j = 0; j < 4; ++j) v[r][j] = __builtin_nontemporal_load(xr + 64 * j); }
; #pragma unroll
;     for (int r = 0; r < R; ++r) { s[r] = 0.f;
; #pragma unroll
;         for (int j = 0; j < 4; ++j) s[r] += (v[r][j].x * v[r][j].x + v[r][j].y * v[r][j].y) + (v[r][j].z * v[r][j].z + v[r][j].w * v[r][j].w); }
; #pragma unroll
;     for (int of = 1; of < 64; of <<= 1) {
; #pragma unroll
;         for (int r = 0; r < R; ++r) s[r] += __shfl_xor(s[r], of); }
; #pragma unroll
;     for (int j = 0; j < 4; ++j) {
;         const f32x4 gg = ((const GAS f32x4*)g)[lane + 64 * j], sh = ((const GAS f32x4*)shift)[lane + 64 * j], sc = ((const GAS f32x4*)scale)[lane + 64 * j];
;         const f32x4 gs = gg * (sc + 1.0f);
.LBB0_128:
	s_add_i32 s4, s16, s14
	s_ashr_i32 s6, s4, 13
	s_mov_b32 s5, 0
	v_lshl_add_u64 v[6:7], s[74:75], 0, v[74:75]
	s_mulk_i32 s6, 0x2400
	global_load_dwordx4 v[58:61], v[6:7], off nt
	global_load_dwordx4 v[34:37], v[6:7], off offset:1024 nt
	global_load_dwordx4 v[22:25], v[6:7], off offset:2048 nt
	s_nop 0
	global_load_dwordx4 v[6:9], v[6:7], off offset:3072 nt
	s_ashr_i32 s7, s6, 31
	s_lshl_b64 s[6:7], s[6:7], 2
	s_add_u32 s6, s58, s6
	v_cmp_lt_i32_e32 vcc, v214, v213
	s_mul_hi_i32 s9, s5, 0xc8
	s_mulk_i32 s5, 0xc8
	s_addc_u32 s7, s59, s7
	v_cndmask_b32_e32 v0, v212, v214, vcc
	v_cmp_lt_i32_e32 vcc, v215, v213
	s_add_u32 s8, s0, s5
	s_addc_u32 s9, s1, s9
	v_cndmask_b32_e32 v5, v212, v215, vcc
	v_cmp_lt_i32_e32 vcc, v216, v213
	s_nop 0
	v_lshl_add_u64 v[88:89], s[6:7], 0, v[74:75]
	s_add_i32 s6, s4, 0x800
	v_cndmask_b32_e32 v10, v212, v216, vcc
	v_cmp_lt_i32_e32 vcc, v217, v213
	s_load_dwordx2 s[8:9], s[8:9], 0x20
	s_ashr_i32 s7, s6, 31
	v_cndmask_b32_e32 v11, v212, v217, vcc
	v_cmp_lt_i32_e32 vcc, v218, v213
	s_lshl_b64 s[10:11], s[6:7], 12
	v_lshlrev_b32_e32 v115, 2, v10
	v_cndmask_b32_e32 v12, v212, v218, vcc
	v_cmp_lt_i32_e32 vcc, v219, v213
	s_add_u32 s10, s72, s10
	v_lshlrev_b32_e32 v116, 2, v11
	v_cndmask_b32_e32 v13, v212, v219, vcc
	v_add_co_u32_e32 v10, vcc, s41, v88
	s_addc_u32 s11, s73, s11
	s_nop 0
	v_addc_co_u32_e32 v11, vcc, 0, v89, vcc
	global_load_dwordx4 v[50:53], v[88:89], off
	global_load_dwordx4 v[94:97], v[10:11], off
	s_add_i32 s20, s4, 0x1000
	v_lshl_add_u64 v[14:15], s[10:11], 0, v[74:75]
	s_waitcnt lgkmcnt(0)
	v_lshl_add_u64 v[92:93], s[8:9], 0, v[74:75]
	v_lshlrev_b32_e32 v117, 2, v12
	v_lshlrev_b32_e32 v118, 2, v13
	s_ashr_i32 s21, s20, 31
	global_load_dwordx4 v[70:73], v[14:15], off nt
	global_load_dwordx4 v[42:45], v[14:15], off offset:1024 nt
	global_load_dwordx4 v[10:13], v[14:15], off offset:3072 nt
	global_load_dwordx4 v[26:29], v[14:15], off offset:2048 nt
	global_load_dwordx4 v[98:101], v[92:93], off
	s_lshl_b64 s[10:11], s[20:21], 12
	s_add_u32 s8, s72, s10
	s_addc_u32 s9, s73, s11
	s_addk_i32 s4, 0x1800
	v_lshl_add_u64 v[14:15], s[8:9], 0, v[74:75]
	s_ashr_i32 s5, s4, 31
	global_load_dwordx4 v[66:69], v[14:15], off nt
	global_load_dwordx4 v[46:49], v[14:15], off offset:1024 nt
	global_load_dwordx4 v[30:33], v[14:15], off offset:2048 nt
	s_nop 0
	global_load_dwordx4 v[14:17], v[14:15], off offset:3072 nt
	s_lshl_b64 s[8:9], s[4:5], 12
	s_add_u32 s8, s72, s8
	s_addc_u32 s9, s73, s9
	v_lshl_add_u64 v[18:19], s[8:9], 0, v[74:75]
	global_load_dwordx4 v[62:65], v[18:19], off nt
	global_load_dwordx4 v[54:57], v[18:19], off offset:1024 nt
	global_load_dwordx4 v[38:41], v[18:19], off offset:2048 nt
	s_nop 0
	global_load_dwordx4 v[18:21], v[18:19], off offset:3072 nt
	v_lshlrev_b32_e32 v114, 2, v0
	v_lshlrev_b32_e32 v5, 2, v5
	s_lshl_b64 s[6:7], s[6:7], 11
	s_add_u32 s6, s62, s6
	v_lshlrev_b64 v[86:87], 3, v[2:3]
	s_addc_u32 s7, s63, s7
	s_lshl_b64 s[8:9], s[20:21], 11
	v_lshl_add_u64 v[82:83], s[6:7], 0, v[86:87]
	s_add_u32 s6, s62, s8
	s_addc_u32 s7, s63, s9
	s_lshl_b64 s[4:5], s[4:5], 11
	s_add_u32 s4, s62, s4
	s_addc_u32 s5, s63, s5
	v_lshl_add_u64 v[80:81], s[76:77], 0, v[86:87]
	v_lshl_add_u64 v[84:85], s[6:7], 0, v[86:87]
	v_lshl_add_u64 v[86:87], s[4:5], 0, v[86:87]
	v_lshl_add_u64 v[90:91], v[88:89], 0, s[48:49]
	s_addk_i32 s14, 0x2000
	s_add_u32 s76, s76, 0x1000000
	s_addc_u32 s77, s77, 0
	s_add_u32 s74, s74, 0x2000000
	s_waitcnt vmcnt(0)
	v_pk_mul_f32 v[102:103], v[60:61], v[60:61]
	v_pk_mul_f32 v[104:105], v[58:59], v[58:59]
	v_pk_mul_f32 v[106:107], v[36:37], v[36:37]
	v_pk_mul_f32 v[108:109], v[34:35], v[34:35]
	v_pk_mov_b32 v[112:113], v[104:105], v[102:103] op_sel:[1,0]
	v_mov_b32_e32 v105, v103
	v_pk_mov_b32 v[102:103], v[108:109], v[106:107] op_sel:[1,0]
	v_mov_b32_e32 v109, v107
	v_mul_f32_e32 v0, v23, v23
	v_mul_f32_e32 v110, v25, v25
	v_pk_add_f32 v[104:105], v[112:113], v[104:105]
	v_pk_add_f32 v[102:103], v[102:103], v[108:109]
	v_mul_f32_e32 v119, v8, v8
	v_mul_f32_e32 v120, v9, v9
	v_mul_f32_e32 v121, v6, v6
	v_mul_f32_e32 v122, v7, v7
	v_pk_fma_f32 v[106:107], v[22:23], v[22:23], v[0:1] op_sel_hi:[1,1,0]
	v_pk_fma_f32 v[110:111], v[24:25], v[24:25], v[110:111] op_sel_hi:[1,1,0]
	v_pk_add_f32 v[104:105], v[104:105], v[104:105] op_sel:[0,1] op_sel_hi:[1,0]
	v_pk_add_f32 v[102:103], v[102:103], v[102:103] op_sel:[0,1] op_sel_hi:[1,0]
	v_mov_b32_e32 v107, v119
	v_mov_b32_e32 v111, v120
	v_mov_b32_e32 v105, v121
	v_mov_b32_e32 v103, v122
	v_pk_add_f32 v[106:107], v[106:107], v[110:111]
	v_pk_add_f32 v[102:103], v[104:105], v[102:103]
	s_addc_u32 s75, s75, 0
	v_pk_add_f32 v[102:103], v[102:103], v[106:107]
	s_cmp_eq_u32 s14, 0x10000
	v_add_f32_e32 v113, v102, v103
	ds_bpermute_b32 v119, v114, v113
	s_waitcnt lgkmcnt(0)
	v_add_f32_e32 v119, v113, v119
	ds_bpermute_b32 v124, v5, v119
	v_pk_add_f32 v[96:97], v[96:97], 1.0 op_sel_hi:[1,0]
	v_pk_add_f32 v[102:103], v[94:95], 1.0 op_sel_hi:[1,0]
	s_waitcnt lgkmcnt(0)
; #define GAS __attribute__((address_space(1)))
; template <int R> __device__ __forceinline__ void norm_rows_bf16(const float* x, bf16* o, int m0, int rstride, const float* g, const float* shift, const float* scale, int lane) {
;     ...
;     for (int r = 0; r < R; ++r) { s[r] = 0.f;
; #pragma unroll
;         for (int j = 0; j < 4; ++j) s[r] += (v[r][j].x * v[r][j].x + v[r][j].y * v[r][j].y) + (v[r][j].z * v[r][j].z + v[r][j].w * v[r][j].w); }
; #pragma unroll
;     for (int of = 1; of < 64; of <<= 1) {
; #pragma unroll
;         for (int r = 0; r < R; ++r) s[r] += __shfl_xor(s[r], of); }
; #pragma unroll
;     for (int j = 0; j < 4; ++j) {
;         const f32x4 gg = ((const GAS f32x4*)g)[lane + 64 * j], sh = ((const GAS f32x4*)shift)[lane + 64 * j], sc = ((const GAS f32x4*)scale)[lane + 64 * j];
;         const f32x4 gs = gg * (sc + 1.0f);
; #pragma unroll
;         for (int r = 0; r < R; ++r) {
;             const float rstd = 1.0f / sqrtf(s[r] * (1.0f / D) + EPS);
	v_add_f32_e32 v119, v119, v124
	v_pk_mul_f32 v[104:105], v[72:73], v[72:73]
	v_pk_mul_f32 v[106:107], v[70:71], v[70:71]
	v_pk_mul_f32 v[108:109], v[44:45], v[44:45]
	v_pk_mul_f32 v[110:111], v[42:43], v[42:43]
	v_mul_f32_e32 v0, v27, v27
	v_mul_f32_e32 v112, v29, v29
	v_pk_mul_f32 v[94:95], v[100:101], v[96:97]
	v_pk_mul_f32 v[96:97], v[98:99], v[102:103]
	v_pk_mov_b32 v[98:99], v[106:107], v[104:105] op_sel:[1,0]
	v_mov_b32_e32 v107, v105
	v_pk_mov_b32 v[100:101], v[110:111], v[108:109] op_sel:[1,0]
	v_mov_b32_e32 v111, v109
	v_mul_f32_e32 v121, v12, v12
	v_mul_f32_e32 v122, v13, v13
	v_pk_fma_f32 v[102:103], v[26:27], v[26:27], v[0:1] op_sel_hi:[1,1,0]
	v_pk_fma_f32 v[104:105], v[28:29], v[28:29], v[112:113] op_sel_hi:[1,1,0]
	v_pk_add_f32 v[98:99], v[98:99], v[106:107]
	v_pk_add_f32 v[100:101], v[100:101], v[110:111]
	v_mul_f32_e32 v120, v10, v10
	v_mul_f32_e32 v123, v11, v11
	v_mov_b32_e32 v103, v121
	v_mov_b32_e32 v105, v122
	v_pk_add_f32 v[98:99], v[98:99], v[98:99] op_sel:[0,1] op_sel_hi:[1,0]
	v_pk_add_f32 v[100:101], v[100:101], v[100:101] op_sel:[0,1] op_sel_hi:[1,0]
	v_pk_add_f32 v[102:103], v[102:103], v[104:105]
	v_mov_b32_e32 v99, v120
	v_mov_b32_e32 v101, v123
	v_pk_mul_f32 v[104:105], v[68:69], v[68:69]
	v_pk_mul_f32 v[106:107], v[66:67], v[66:67]
	v_pk_mul_f32 v[108:109], v[48:49], v[48:49]
	v_pk_mul_f32 v[110:111], v[46:47], v[46:47]
	v_mul_f32_e32 v0, v31, v31
	v_mul_f32_e32 v112, v33, v33
	v_pk_add_f32 v[98:99], v[98:99], v[100:101]
	v_pk_mov_b32 v[100:101], v[106:107], v[104:105] op_sel:[1,0]
	v_mov_b32_e32 v107, v105
	v_pk_mov_b32 v[104:105], v[110:111], v[108:109] op_sel:[1,0]
	v_mov_b32_e32 v111, v109
	v_mul_f32_e32 v120, v16, v16
	v_mul_f32_e32 v121, v17, v17
	v_pk_fma_f32 v[108:109], v[30:31], v[30:31], v[0:1] op_sel_hi:[1,1,0]
	v_pk_fma_f32 v[112:113], v[32:33], v[32:33], v[112:113] op_sel_hi:[1,1,0]
	v_pk_add_f32 v[98:99], v[98:99], v[102:103]
	v_pk_add_f32 v[100:101], v[100:101], v[106:107]
	v_pk_add_f32 v[102:103], v[104:105], v[110:111]
	v_mul_f32_e32 v122, v14, v14
	v_mul_f32_e32 v123, v15, v15
	v_mov_b32_e32 v109, v120
	v_mov_b32_e32 v113, v121
	v_pk_add_f32 v[100:101], v[100:101], v[100:101] op_sel:[0,1] op_sel_hi:[1,0]
	v_pk_add_f32 v[102:103], v[102:103], v[102:103] op_sel:[0,1] op_sel_hi:[1,0]
	ds_bpermute_b32 v120, v115, v119
	v_pk_add_f32 v[104:105], v[108:109], v[112:113]
	v_add_f32_e32 v121, v98, v99
	v_mov_b32_e32 v101, v122
	v_mov_b32_e32 v103, v123
	v_pk_mul_f32 v[98:99], v[64:65], v[64:65]
	v_pk_mul_f32 v[106:107], v[62:63], v[62:63]
	v_pk_mul_f32 v[108:109], v[56:57], v[56:57]
	v_pk_mul_f32 v[110:111], v[54:55], v[54:55]
	ds_bpermute_b32 v126, v114, v121
	v_pk_add_f32 v[100:101], v[100:101], v[102:103]
	v_pk_mov_b32 v[102:103], v[106:107], v[98:99] op_sel:[1,0]
	v_mov_b32_e32 v107, v99
	v_pk_mov_b32 v[98:99], v[110:111], v[108:109] op_sel:[1,0]
	v_mov_b32_e32 v111, v109
	v_pk_add_f32 v[102:103], v[102:103], v[106:107]
	v_pk_add_f32 v[98:99], v[98:99], v[110:111]
	v_mul_f32_e32 v0, v39, v39
	v_mul_f32_e32 v112, v41, v41
	v_mul_f32_e32 v124, v18, v18
	v_mul_f32_e32 v125, v19, v19
	v_pk_add_f32 v[100:101], v[100:101], v[104:105]
	v_pk_add_f32 v[102:103], v[102:103], v[102:103] op_sel:[0,1] op_sel_hi:[1,0]
	v_pk_add_f32 v[98:99], v[98:99], v[98:99] op_sel:[0,1] op_sel_hi:[1,0]
	v_mul_f32_e32 v122, v20, v20
	v_mul_f32_e32 v123, v21, v21
	v_pk_fma_f32 v[108:109], v[38:39], v[38:39], v[0:1] op_sel_hi:[1,1,0]
	v_pk_fma_f32 v[112:113], v[40:41], v[40:41], v[112:113] op_sel_hi:[1,1,0]
	v_add_f32_e32 v0, v100, v101
	v_mov_b32_e32 v103, v124
	v_mov_b32_e32 v99, v125
	s_waitcnt lgkmcnt(1)
	v_add_f32_e32 v100, v119, v120
	v_mov_b32_e32 v109, v122
	v_mov_b32_e32 v113, v123
	v_pk_add_f32 v[98:99], v[102:103], v[98:99]
	ds_bpermute_b32 v102, v116, v100
	v_pk_add_f32 v[104:105], v[108:109], v[112:113]
	ds_bpermute_b32 v101, v114, v0
	s_waitcnt lgkmcnt(2)
	v_add_f32_e32 v103, v121, v126
	v_pk_add_f32 v[98:99], v[98:99], v[104:105]
	ds_bpermute_b32 v104, v5, v103
	v_add_f32_e32 v98, v98, v99
	ds_bpermute_b32 v99, v114, v98
	s_waitcnt lgkmcnt(3)
	v_add_f32_e32 v100, v100, v102
	s_waitcnt lgkmcnt(2)
	v_add_f32_e32 v0, v0, v101
	ds_bpermute_b32 v102, v117, v100
	ds_bpermute_b32 v101, v5, v0
	s_waitcnt lgkmcnt(3)
	v_add_f32_e32 v103, v103, v104
	ds_bpermute_b32 v104, v115, v103
	s_waitcnt lgkmcnt(3)
	v_add_f32_e32 v98, v98, v99
	ds_bpermute_b32 v5, v5, v98
	s_waitcnt lgkmcnt(3)
	v_add_f32_e32 v99, v100, v102
	s_waitcnt lgkmcnt(2)
	v_add_f32_e32 v0, v0, v101
	ds_bpermute_b32 v101, v118, v99
	s_waitcnt lgkmcnt(2)
	v_add_f32_e32 v102, v103, v104
	ds_bpermute_b32 v100, v115, v0
	ds_bpermute_b32 v103, v116, v102
	s_waitcnt lgkmcnt(3)
	v_add_f32_e32 v5, v98, v5
	ds_bpermute_b32 v98, v115, v5
	s_waitcnt lgkmcnt(3)
	v_add_f32_e32 v99, v99, v101
	v_fmamk_f32 v99, v99, 0x3a800000, v220
	s_waitcnt lgkmcnt(2)
	v_add_f32_e32 v0, v0, v100
	s_waitcnt lgkmcnt(1)
	v_add_f32_e32 v101, v102, v103
	v_mul_f32_e32 v102, 0x4f800000, v99
	v_cmp_gt_f32_e32 vcc, s45, v99
	ds_bpermute_b32 v100, v116, v0
	ds_bpermute_b32 v103, v117, v101
	v_cndmask_b32_e32 v99, v99, v102, vcc
	s_waitcnt lgkmcnt(2)
	v_add_f32_e32 v5, v5, v98
	v_sqrt_f32_e32 v98, v99
	ds_bpermute_b32 v102, v116, v5
	s_waitcnt lgkmcnt(2)
	v_add_f32_e32 v0, v0, v100
	s_waitcnt lgkmcnt(1)
	v_add_f32_e32 v101, v101, v103
	v_add_u32_e32 v103, -1, v98
	ds_bpermute_b32 v100, v117, v0
	v_add_u32_e32 v104, 1, v98
	v_fma_f32 v106, -v103, v98, v99
	ds_bpermute_b32 v105, v118, v101
	v_fma_f32 v107, -v104, v98, v99
	s_waitcnt lgkmcnt(2)
	v_add_f32_e32 v5, v5, v102
	v_cmp_ge_f32_e64 s[4:5], 0, v106
	ds_bpermute_b32 v102, v117, v5
	s_waitcnt lgkmcnt(2)
; __device__ __forceinline__ unsigned cvtpk(float lo, float hi) { f32x2 v = {lo, hi}; bf16x2_t b = __builtin_convertvector(v, bf16x2_t); return __builtin_bit_cast(unsigned, b); }
; #define GAS __attribute__((address_space(1)))
; template <int R> __device__ __forceinline__ void norm_rows_bf16(const float* x, bf16* o, int m0, int rstride, const float* g, const float* shift, const float* scale, int lane) {
;     ...
;     for (int j = 0; j < 4; ++j) {
;         const f32x4 gg = ((const GAS f32x4*)g)[lane + 64 * j], sh = ((const GAS f32x4*)shift)[lane + 64 * j], sc = ((const GAS f32x4*)scale)[lane + 64 * j];
;         const f32x4 gs = gg * (sc + 1.0f);
; #pragma unroll
;         for (int r = 0; r < R; ++r) {
;             const float rstd = 1.0f / sqrtf(s[r] * (1.0f / D) + EPS);
;             const f32x4 y = v[r][j] * rstd * gs + sh;
;             u32x2 w; w.x = cvtpk(y.x, y.y); w.y = cvtpk(y.z, y.w); ((GAS u32x2*)(o + (size_t)(m0 + r * rstride) * D) + lane)[64 * j] = w;
;         }
;     }
	v_add_f32_e32 v0, v0, v100
	v_cndmask_b32_e64 v98, v98, v103, s[4:5]
	v_cmp_lt_f32_e64 s[4:5], 0, v107
	ds_bpermute_b32 v100, v118, v0
	s_waitcnt lgkmcnt(2)
	v_add_f32_e32 v101, v101, v105
	v_cndmask_b32_e64 v98, v98, v104, s[4:5]
	v_mul_f32_e32 v103, 0x37800000, v98
	v_cndmask_b32_e32 v98, v98, v103, vcc
	v_cmp_class_f32_e32 vcc, v99, v221
	v_fmamk_f32 v101, v101, 0x3a800000, v220
	s_waitcnt lgkmcnt(1)
	v_add_f32_e32 v5, v5, v102
	v_cndmask_b32_e32 v98, v98, v99, vcc
	v_div_scale_f32 v102, s[4:5], v98, v98, 1.0
	v_mul_f32_e32 v99, 0x4f800000, v101
	v_cmp_gt_f32_e64 s[4:5], s45, v101
	v_rcp_f32_e32 v104, v102
	s_waitcnt lgkmcnt(0)
	v_add_f32_e32 v0, v0, v100
	v_cndmask_b32_e64 v99, v101, v99, s[4:5]
	v_sqrt_f32_e32 v105, v99
	ds_bpermute_b32 v101, v118, v5
	v_fmamk_f32 v0, v0, 0x3a800000, v220
	v_mul_f32_e32 v100, 0x4f800000, v0
	v_cmp_gt_f32_e64 s[6:7], s45, v0
	v_add_u32_e32 v106, -1, v105
	v_div_scale_f32 v103, vcc, 1.0, v98, 1.0
	v_cndmask_b32_e64 v100, v0, v100, s[6:7]
	v_fma_f32 v0, -v102, v104, 1.0
	v_add_u32_e32 v107, 1, v105
	v_sqrt_f32_e32 v108, v100
	v_fmac_f32_e32 v104, v0, v104
	v_fma_f32 v0, -v106, v105, v99
	s_waitcnt lgkmcnt(0)
	v_add_f32_e32 v5, v5, v101
	v_fma_f32 v101, -v107, v105, v99
	v_mul_f32_e32 v109, v103, v104
	v_cmp_ge_f32_e64 s[8:9], 0, v0
	v_fmamk_f32 v5, v5, 0x3a800000, v220
	v_cmp_gt_f32_e64 s[10:11], s45, v5
	v_cndmask_b32_e64 v0, v105, v106, s[8:9]
	v_cmp_lt_f32_e64 s[8:9], 0, v101
	v_fma_f32 v105, -v102, v109, v103
	v_mul_f32_e32 v101, 0x4f800000, v5
	v_fmac_f32_e32 v109, v105, v104
	v_cndmask_b32_e64 v0, v0, v107, s[8:9]
	v_cndmask_b32_e64 v5, v5, v101, s[10:11]
	v_add_u32_e32 v101, -1, v108
	v_fma_f32 v102, -v102, v109, v103
	v_mul_f32_e32 v103, 0x37800000, v0
	v_add_u32_e32 v105, 1, v108
	v_sqrt_f32_e32 v106, v5
	v_cndmask_b32_e64 v103, v0, v103, s[4:5]
	v_fma_f32 v0, -v101, v108, v100
	v_fma_f32 v107, -v105, v108, v100
	v_div_fmas_f32 v102, v102, v104, v109
	v_cmp_ge_f32_e32 vcc, 0, v0
	v_cmp_class_f32_e64 s[4:5], v99, v221
	v_div_fixup_f32 v0, v102, v98, 1.0
	v_cndmask_b32_e32 v101, v108, v101, vcc
	v_cmp_lt_f32_e32 vcc, 0, v107
	v_cndmask_b32_e64 v98, v103, v99, s[4:5]
	v_div_scale_f32 v99, s[4:5], v98, v98, 1.0
	v_cndmask_b32_e32 v101, v101, v105, vcc
	v_add_u32_e32 v103, -1, v106
	v_mul_f32_e32 v107, 0x37800000, v101
	v_pk_mul_f32 v[58:59], v[58:59], v[0:1] op_sel_hi:[1,0]
	v_pk_mul_f32 v[60:61], v[60:61], v[0:1] op_sel_hi:[1,0]
	v_add_u32_e32 v104, 1, v106
	v_rcp_f32_e32 v105, v99
	v_cndmask_b32_e64 v101, v101, v107, s[6:7]
	v_fma_f32 v107, -v103, v106, v5
	v_pk_fma_f32 v[60:61], v[94:95], v[60:61], v[52:53]
	v_pk_fma_f32 v[58:59], v[96:97], v[58:59], v[50:51]
	v_cmp_class_f32_e32 vcc, v100, v221
	v_fma_f32 v108, -v104, v106, v5
	v_cmp_ge_f32_e64 s[6:7], 0, v107
	v_cvt_pk_bf16_f32 v58, v58, v59
	v_cvt_pk_bf16_f32 v59, v60, v61
	v_cndmask_b32_e64 v60, v106, v103, s[6:7]
	v_cmp_lt_f32_e64 s[6:7], 0, v108
	v_cndmask_b32_e32 v100, v101, v100, vcc
	global_store_dwordx2 v[80:81], v[58:59], off
	v_div_scale_f32 v59, s[8:9], v100, v100, 1.0
	v_cndmask_b32_e64 v58, v60, v104, s[6:7]
	v_fma_f32 v60, -v99, v105, 1.0
	v_rcp_f32_e32 v103, v59
	v_mul_f32_e32 v61, 0x37800000, v58
	v_div_scale_f32 v102, s[4:5], 1.0, v98, 1.0
	v_cndmask_b32_e64 v58, v58, v61, s[10:11]
	v_cmp_class_f32_e32 vcc, v5, v221
	v_fmac_f32_e32 v105, v60, v105
	v_mul_f32_e32 v60, v102, v105
	v_cndmask_b32_e32 v5, v58, v5, vcc
	v_fma_f32 v58, -v99, v60, v102
	v_div_scale_f32 v104, s[6:7], v5, v5, 1.0
	v_fmac_f32_e32 v60, v58, v105
	v_fma_f32 v58, -v59, v103, 1.0
	v_rcp_f32_e32 v107, v104
	v_div_scale_f32 v101, s[8:9], 1.0, v100, 1.0
	v_fma_f32 v61, -v99, v60, v102
	v_fmac_f32_e32 v103, v58, v103
	s_mov_b64 vcc, s[4:5]
	v_div_fmas_f32 v58, v61, v105, v60
	v_mul_f32_e32 v99, v101, v103
	v_div_fixup_f32 v58, v58, v98, 1.0
	v_fma_f32 v98, -v59, v99, v101
	v_pk_mul_f32 v[60:61], v[70:71], v[58:59] op_sel_hi:[1,0]
	v_pk_mul_f32 v[70:71], v[72:73], v[58:59] op_sel_hi:[1,0]
	v_fmac_f32_e32 v99, v98, v103
	v_fma_f32 v72, -v104, v107, 1.0
	v_div_scale_f32 v106, s[6:7], 1.0, v5, 1.0
	v_fma_f32 v59, -v59, v99, v101
	v_fmac_f32_e32 v107, v72, v107
	s_mov_b64 vcc, s[8:9]
	v_pk_fma_f32 v[70:71], v[94:95], v[70:71], v[52:53]
	v_pk_fma_f32 v[60:61], v[96:97], v[60:61], v[50:51]
	v_div_fmas_f32 v59, v59, v103, v99
	v_mul_f32_e32 v72, v106, v107
	v_cvt_pk_bf16_f32 v60, v60, v61
	v_cvt_pk_bf16_f32 v61, v70, v71
	v_div_fixup_f32 v70, v59, v100, 1.0
	v_fma_f32 v59, -v104, v72, v106
	v_fmac_f32_e32 v72, v59, v107
	global_store_dwordx2 v[82:83], v[60:61], off
	v_pk_mul_f32 v[60:61], v[66:67], v[70:71] op_sel_hi:[1,0]
	v_pk_mul_f32 v[66:67], v[68:69], v[70:71] op_sel_hi:[1,0]
	v_fma_f32 v59, -v104, v72, v106
	s_mov_b64 vcc, s[6:7]
	v_pk_fma_f32 v[66:67], v[94:95], v[66:67], v[52:53]
	v_pk_fma_f32 v[60:61], v[96:97], v[60:61], v[50:51]
	v_div_fmas_f32 v59, v59, v107, v72
	v_cvt_pk_bf16_f32 v60, v60, v61
	v_cvt_pk_bf16_f32 v61, v66, v67
	v_div_fixup_f32 v68, v59, v5, 1.0
	global_store_dwordx2 v[84:85], v[60:61], off
	v_pk_mul_f32 v[60:61], v[62:63], v[68:69] op_sel_hi:[1,0]
	v_pk_mul_f32 v[62:63], v[64:65], v[68:69] op_sel_hi:[1,0]
	v_pk_fma_f32 v[50:51], v[96:97], v[60:61], v[50:51]
	v_pk_fma_f32 v[52:53], v[94:95], v[62:63], v[52:53]
	v_cvt_pk_bf16_f32 v50, v50, v51
	v_cvt_pk_bf16_f32 v51, v52, v53
	global_store_dwordx2 v[86:87], v[50:51], off
	global_load_dwordx4 v[50:53], v[90:91], off offset:1024
	s_nop 0
	global_load_dwordx4 v[60:63], v[92:93], off offset:1024
	global_load_dwordx4 v[64:67], v[88:89], off offset:1024
	v_pk_mul_f32 v[34:35], v[34:35], v[0:1] op_sel_hi:[1,0]
	v_pk_mul_f32 v[36:37], v[36:37], v[0:1] op_sel_hi:[1,0]
	v_pk_mul_f32 v[42:43], v[42:43], v[58:59] op_sel_hi:[1,0]
	v_pk_mul_f32 v[44:45], v[44:45], v[58:59] op_sel_hi:[1,0]
	v_pk_mul_f32 v[46:47], v[46:47], v[70:71] op_sel_hi:[1,0]
	v_pk_mul_f32 v[48:49], v[48:49], v[70:71] op_sel_hi:[1,0]
	v_pk_mul_f32 v[54:55], v[54:55], v[68:69] op_sel_hi:[1,0]
	v_pk_mul_f32 v[56:57], v[56:57], v[68:69] op_sel_hi:[1,0]
	v_pk_mul_f32 v[22:23], v[22:23], v[0:1] op_sel_hi:[1,0]
	v_pk_mul_f32 v[24:25], v[24:25], v[0:1] op_sel_hi:[1,0]
	v_pk_mul_f32 v[26:27], v[26:27], v[58:59] op_sel_hi:[1,0]
	v_pk_mul_f32 v[28:29], v[28:29], v[58:59] op_sel_hi:[1,0]
	v_pk_mul_f32 v[30:31], v[30:31], v[70:71] op_sel_hi:[1,0]
	v_pk_mul_f32 v[32:33], v[32:33], v[70:71] op_sel_hi:[1,0]
	v_pk_mul_f32 v[38:39], v[38:39], v[68:69] op_sel_hi:[1,0]
	v_pk_mul_f32 v[40:41], v[40:41], v[68:69] op_sel_hi:[1,0]
	v_pk_mul_f32 v[6:7], v[6:7], v[0:1] op_sel_hi:[1,0]
	v_pk_mul_f32 v[8:9], v[8:9], v[0:1] op_sel_hi:[1,0]
	v_pk_mul_f32 v[10:11], v[10:11], v[58:59] op_sel_hi:[1,0]
	v_pk_mul_f32 v[12:13], v[12:13], v[58:59] op_sel_hi:[1,0]
	v_pk_mul_f32 v[14:15], v[14:15], v[70:71] op_sel_hi:[1,0]
	v_pk_mul_f32 v[16:17], v[16:17], v[70:71] op_sel_hi:[1,0]
	v_pk_mul_f32 v[18:19], v[18:19], v[68:69] op_sel_hi:[1,0]
	v_pk_mul_f32 v[20:21], v[20:21], v[68:69] op_sel_hi:[1,0]
	s_waitcnt vmcnt(2)
; __device__ __forceinline__ unsigned cvtpk(float lo, float hi) { f32x2 v = {lo, hi}; bf16x2_t b = __builtin_convertvector(v, bf16x2_t); return __builtin_bit_cast(unsigned, b); }
; #define GAS __attribute__((address_space(1)))
; template <int R> __device__ __forceinline__ void norm_rows_bf16(const float* x, bf16* o, int m0, int rstride, const float* g, const float* shift, const float* scale, int lane) {
;     ...
;     for (int j = 0; j < 4; ++j) {
;         const f32x4 gg = ((const GAS f32x4*)g)[lane + 64 * j], sh = ((const GAS f32x4*)shift)[lane + 64 * j], sc = ((const GAS f32x4*)scale)[lane + 64 * j];
;         const f32x4 gs = gg * (sc + 1.0f);
; #pragma unroll
;         for (int r = 0; r < R; ++r) {
;             const float rstd = 1.0f / sqrtf(s[r] * (1.0f / D) + EPS);
;             const f32x4 y = v[r][j] * rstd * gs + sh;
;             u32x2 w; w.x = cvtpk(y.x, y.y); w.y = cvtpk(y.z, y.w); ((GAS u32x2*)(o + (size_t)(m0 + r * rstride) * D) + lane)[64 * j] = w;
;         }
;     }
	v_pk_add_f32 v[52:53], v[52:53], 1.0 op_sel_hi:[1,0]
	v_pk_add_f32 v[50:51], v[50:51], 1.0 op_sel_hi:[1,0]
	s_waitcnt vmcnt(1)
	v_pk_mul_f32 v[52:53], v[62:63], v[52:53]
	v_pk_mul_f32 v[50:51], v[60:61], v[50:51]
	s_waitcnt vmcnt(0)
	v_pk_fma_f32 v[36:37], v[36:37], v[52:53], v[66:67]
	v_pk_fma_f32 v[34:35], v[34:35], v[50:51], v[64:65]
	v_pk_fma_f32 v[44:45], v[44:45], v[52:53], v[66:67]
	v_pk_fma_f32 v[48:49], v[48:49], v[52:53], v[66:67]
	v_pk_fma_f32 v[52:53], v[56:57], v[52:53], v[66:67]
	v_pk_fma_f32 v[42:43], v[42:43], v[50:51], v[64:65]
	v_pk_fma_f32 v[46:47], v[46:47], v[50:51], v[64:65]
	v_pk_fma_f32 v[50:51], v[54:55], v[50:51], v[64:65]
	v_cvt_pk_bf16_f32 v34, v34, v35
	v_cvt_pk_bf16_f32 v35, v36, v37
	v_cvt_pk_bf16_f32 v36, v42, v43
	v_cvt_pk_bf16_f32 v37, v44, v45
	v_cvt_pk_bf16_f32 v42, v46, v47
	v_cvt_pk_bf16_f32 v43, v48, v49
	v_cvt_pk_bf16_f32 v44, v50, v51
	v_cvt_pk_bf16_f32 v45, v52, v53
	global_store_dwordx2 v[80:81], v[34:35], off offset:512
	global_store_dwordx2 v[82:83], v[36:37], off offset:512
	global_store_dwordx2 v[84:85], v[42:43], off offset:512
	global_store_dwordx2 v[86:87], v[44:45], off offset:512
	global_load_dwordx4 v[34:37], v[90:91], off offset:2048
	s_nop 0
	global_load_dwordx4 v[42:45], v[92:93], off offset:2048
	global_load_dwordx4 v[46:49], v[88:89], off offset:2048
	s_waitcnt vmcnt(2)
	v_pk_add_f32 v[36:37], v[36:37], 1.0 op_sel_hi:[1,0]
	v_pk_add_f32 v[34:35], v[34:35], 1.0 op_sel_hi:[1,0]
	s_waitcnt vmcnt(1)
	v_pk_mul_f32 v[36:37], v[44:45], v[36:37]
	v_pk_mul_f32 v[34:35], v[42:43], v[34:35]
	s_waitcnt vmcnt(0)
	v_pk_fma_f32 v[24:25], v[24:25], v[36:37], v[48:49]
	v_pk_fma_f32 v[22:23], v[22:23], v[34:35], v[46:47]
	v_pk_fma_f32 v[28:29], v[28:29], v[36:37], v[48:49]
	v_pk_fma_f32 v[32:33], v[32:33], v[36:37], v[48:49]
	v_pk_fma_f32 v[36:37], v[40:41], v[36:37], v[48:49]
	v_pk_fma_f32 v[26:27], v[26:27], v[34:35], v[46:47]
	v_pk_fma_f32 v[30:31], v[30:31], v[34:35], v[46:47]
	v_pk_fma_f32 v[34:35], v[38:39], v[34:35], v[46:47]
	v_cvt_pk_bf16_f32 v22, v22, v23
	v_cvt_pk_bf16_f32 v23, v24, v25
	v_cvt_pk_bf16_f32 v24, v26, v27
	v_cvt_pk_bf16_f32 v25, v28, v29
	v_cvt_pk_bf16_f32 v26, v30, v31
	v_cvt_pk_bf16_f32 v27, v32, v33
	v_cvt_pk_bf16_f32 v28, v34, v35
	v_cvt_pk_bf16_f32 v29, v36, v37
	global_store_dwordx2 v[80:81], v[22:23], off offset:1024
	global_store_dwordx2 v[82:83], v[24:25], off offset:1024
	global_store_dwordx2 v[84:85], v[26:27], off offset:1024
	global_store_dwordx2 v[86:87], v[28:29], off offset:1024
	global_load_dwordx4 v[22:25], v[90:91], off offset:3072
	s_nop 0
	global_load_dwordx4 v[26:29], v[92:93], off offset:3072
	global_load_dwordx4 v[30:33], v[88:89], off offset:3072
	s_waitcnt vmcnt(2)
	v_pk_add_f32 v[24:25], v[24:25], 1.0 op_sel_hi:[1,0]
	v_pk_add_f32 v[22:23], v[22:23], 1.0 op_sel_hi:[1,0]
	s_waitcnt vmcnt(1)
	v_pk_mul_f32 v[24:25], v[28:29], v[24:25]
	v_pk_mul_f32 v[22:23], v[26:27], v[22:23]
	s_waitcnt vmcnt(0)
	v_pk_fma_f32 v[8:9], v[8:9], v[24:25], v[32:33]
	v_pk_fma_f32 v[6:7], v[6:7], v[22:23], v[30:31]
	v_pk_fma_f32 v[12:13], v[12:13], v[24:25], v[32:33]
	v_pk_fma_f32 v[10:11], v[10:11], v[22:23], v[30:31]
	v_pk_fma_f32 v[16:17], v[16:17], v[24:25], v[32:33]
	v_pk_fma_f32 v[14:15], v[14:15], v[22:23], v[30:31]
	v_pk_fma_f32 v[20:21], v[20:21], v[24:25], v[32:33]
	v_pk_fma_f32 v[18:19], v[18:19], v[22:23], v[30:31]
	v_cvt_pk_bf16_f32 v6, v6, v7
	v_cvt_pk_bf16_f32 v7, v8, v9
	v_cvt_pk_bf16_f32 v8, v10, v11
	v_cvt_pk_bf16_f32 v9, v12, v13
	v_cvt_pk_bf16_f32 v10, v14, v15
	v_cvt_pk_bf16_f32 v11, v16, v17
	v_cvt_pk_bf16_f32 v12, v18, v19
	v_cvt_pk_bf16_f32 v13, v20, v21
	global_store_dwordx2 v[80:81], v[6:7], off offset:1536
	global_store_dwordx2 v[82:83], v[8:9], off offset:1536
	global_store_dwordx2 v[84:85], v[10:11], off offset:1536
	global_store_dwordx2 v[86:87], v[12:13], off offset:1536
	s_cbranch_scc0 .LBB0_128
	s_branch .LBB0_119
